# v33 staggered DMA-ring attention plus static s_setprio 1 for the leading half (waves 0-3) inside the KV loop
# speedup vs baseline: 1.0046x; 1.0046x over previous
; __device__ __forceinline__ int opaque_tid() { int t = (int)threadIdx.x; asm volatile("" : "+v"(t)); return t; }
; __device__ __forceinline__ int v_st(int k, int c) { const int kk = (k & ~0xC) | ((k & 4) << 1) | ((k & 8) >> 1); return ((kk >> 3) * 4 + (c >> 5)) * 512 + ((kk & 7) * 32 + (c & 31)) * 2; }
; __device__ __forceinline__ int v_rd_base(int lane) { return ((lane & 3) << 3) | (((lane >> 2) & 3) << 6) | (((lane >> 4) & 1) << 5) | (((lane >> 5) & 1) << 8); }
; #define SLOAD(i, k0) do { sr_[i].vs0 = St::ld8(&Vh[(long)((k0) + sr) * LDK + sc]); sr_[i].vs1 = St::ld8(&Vh[(long)((k0) + 32 + sr) * LDK + sc]); \
;     sr_[i].ks0 = St::ld8(&Kh[(long)((k0) + sr) * LDK + sc]); sr_[i].ks1 = St::ld8(&Kh[(long)((k0) + 32 + sr) * LDK + sc]); } while (0)
; template <typename TQ>
; __device__ __forceinline__ void attn_dense_body(const TQ* __restrict__ Qb, const bf16* __restrict__ Kh, const bf16* __restrict__ Vh,
;                                                 unsigned short* __restrict__ Ob, int seq, char* lds) {
;     ...
;   const int tid = ::opaque_tid(), wid = tid >> 6, lane = tid & 63, r32 = lane & 31, hi = lane >> 5;
;   bf16* V_lds = (bf16*)lds; bf16* K_lds = (bf16*)(lds + 2 * SHM_V);
;   float* ws = (float*)(lds + 2 * SHM_V + 2 * SHM_K) + wid * 64; float* li_l = ws; float* al_l = ws + 32;
;   float m_reg = -1e30f, l_reg = 0; f32x16 o[4] = {}; bf16x8 qr[8];
;   const TQ* Qw = Qb + (long)(wid * QBLK + r32) * LDQ + hi * 8;
; #pragma unroll
;   for (int d0 = 0; d0 < 8; ++d0) qr[d0] = SQ::tobf(SQ::ld8(Qw + d0 * 16));
;   const int sr = tid >> 4, sc = (tid & 15) * 8, vst0 = v_st(sr, sc), vst1 = v_st(32 + sr, sc);
;   const int vb0 = (int)(uintptr_t)V_lds + v_rd_base(lane);
;   struct { typename St::T vs0, vs1, ks0, ks1; } sr_[SDEPTH];
;     ...
;   f32x16 pA0, pA1, pB0, pB1; float mnA, mnB, alA, alB; bf16x8 pa0, pa1, pa2, pa3; const int NT = seq / KVBLK;
;   constexpr int SE = 0, SO = SDEPTH - 1;
;   SLOAD(SE, 0); asm volatile("s_waitcnt vmcnt(0)" ::: "memory"); SWRITE(0, SE); __syncthreads();
;   qkt(pA0, pA1, K_lds, qr, r32, hi); partialSM(pA0, pA1, m_reg, mnA, alA);
.LBB0_75:
	s_lshl_b64 s[40:41], s[0:1], 1
	v_readlane_b32 s0, v254, 41
	v_readlane_b32 s1, v254, 42
	s_add_u32 s46, s0, s40
	v_mov_b32_e32 v74, v211
	s_addc_u32 s47, s1, s41
	s_lshl_b64 s[0:1], s[38:39], 1
	s_add_u32 s38, s58, s0
	v_ashrrev_i32_e32 v16, 4, v74
	v_lshlrev_b32_e32 v22, 3, v74
	v_add_u32_e32 v18, 32, v16
	s_addc_u32 s39, s59, s1
	v_and_b32_e32 v176, 0x78, v22
	v_ashrrev_i32_e32 v17, 31, v16
	v_ashrrev_i32_e32 v19, 31, v18
	s_add_u32 s42, s24, s0
	v_lshlrev_b32_e32 v23, 1, v176
	v_lshlrev_b64 v[48:49], 8, v[16:17]
	v_lshlrev_b64 v[8:9], 8, v[18:19]
	s_addc_u32 s43, s25, s1
	s_mov_b64 s[6:7], s[38:39]
	s_mov_b64 s[68:69], s[42:43]
	v_or_b32_e32 v50, v48, v23
	v_mov_b32_e32 v51, v49
	v_or_b32_e32 v8, v8, v23
	v_ashrrev_i32_e32 v183, 6, v74
	s_waitcnt lgkmcnt(0)
	v_lshl_add_u64 v[0:1], s[42:43], 0, v[50:51]
	v_lshl_add_u64 v[4:5], s[42:43], 0, v[8:9]
	v_lshl_add_u64 v[10:11], s[38:39], 0, v[50:51]
	v_lshl_add_u64 v[12:13], s[38:39], 0, v[8:9]
	v_and_b32_e32 v179, 31, v74
	v_lshlrev_b32_e32 v178, 5, v183
	global_load_dwordx4 v[0:3], v[0:1], off
	s_nop 0
	global_load_dwordx4 v[4:7], v[4:5], off
	s_nop 0
	global_load_dwordx4 v[8:11], v[10:11], off
	s_nop 0
	global_load_dwordx4 v[12:15], v[12:13], off
	v_or_b32_e32 v20, v178, v179
	v_ashrrev_i32_e32 v21, 31, v20
	v_bfe_u32 v182, v74, 5, 1
	v_lshlrev_b64 v[20:21], 11, v[20:21]
	v_lshl_add_u64 v[20:21], s[46:47], 0, v[20:21]
	v_lshlrev_b32_e32 v208, 4, v182
	v_lshl_add_u64 v[20:21], v[20:21], 0, v[208:209]
	global_load_dwordx4 v[112:115], v[20:21], off
	global_load_dwordx4 v[108:111], v[20:21], off offset:32
	global_load_dwordx4 v[120:123], v[20:21], off offset:64
	global_load_dwordx4 v[124:127], v[20:21], off offset:96
	global_load_dwordx4 v[116:119], v[20:21], off offset:128
	global_load_dwordx4 v[104:107], v[20:21], off offset:160
	global_load_dwordx4 v[100:103], v[20:21], off offset:192
	global_load_dwordx4 v[96:99], v[20:21], off offset:224
	v_and_b32_e32 v19, 0xfffff0, v16
	v_lshlrev_b32_e32 v24, 1, v16
	v_lshrrev_b32_e32 v25, 1, v16
	v_and_b32_e32 v26, 3, v16
	v_and_or_b32 v19, v24, 8, v19
	v_and_or_b32 v24, v25, 4, v26
	v_and_b32_e32 v25, 0xfffff0, v18
	v_lshlrev_b32_e32 v26, 1, v18
	v_and_b32_e32 v17, 0x70, v74
	v_bfe_u32 v22, v22, 5, 2
	v_lshlrev_b32_e32 v16, 8, v16
	v_lshlrev_b32_e32 v18, 8, v18
	v_lshrrev_b32_e32 v19, 1, v19
	v_and_or_b32 v25, v26, 8, v25
	v_lshlrev_b32_e32 v52, 4, v74
	v_bitop3_b32 v16, v23, v16, v17 bitop3:0xde
	v_bitop3_b32 v17, v23, v18, v17 bitop3:0xde
	v_or_b32_e32 v18, v19, v22
	v_lshrrev_b32_e32 v19, 1, v25
	v_lshlrev_b32_e32 v68, 8, v179
	v_and_b32_e32 v69, 0x70, v52
	v_lshlrev_b32_e32 v24, 6, v24
	v_and_b32_e32 v28, 48, v23
	v_add_u32_e32 v189, 0, v16
	v_add_u32_e32 v190, 0, v17
	v_lshlrev_b32_e32 v16, 9, v18
	v_or_b32_e32 v17, v19, v22
	v_bitop3_b32 v27, v208, v68, v69 bitop3:0xde
	v_or3_b32 v16, v16, v24, v28
	v_lshlrev_b32_e32 v17, 9, v17
	v_or3_b32 v17, v17, v24, v28
	v_add_u32_e32 v191, 0, v16
	v_add_u32_e32 v193, 0, v27
	s_waitcnt vmcnt(0)
	v_add_u32_e32 v192, 0, v17
	s_mov_b64 s[28:29], 0x4000
	s_add_i32 s3, 0, 0x20800
	v_and_b32_e32 v71, 0xc0, v52
	v_and_b32_e32 v177, 63, v74
	v_lshlrev_b32_e32 v70, 3, v177
	s_mov_b32 s4, 0x42b504f3
	s_cmp_lg_u32 0, -1
	s_mov_b32 s72, s73
	s_mov_b32 s74, s73
	s_mov_b32 s75, s73
	s_waitcnt vmcnt(0)
	ds_write_b128 v191, v[0:3]
	s_waitcnt vmcnt(10)
	ds_write_b128 v192, v[4:7]
	s_waitcnt vmcnt(9)
	ds_write_b128 v189, v[8:11] offset:32768
	s_waitcnt vmcnt(8)
	ds_write_b128 v190, v[12:15] offset:32768
	s_waitcnt lgkmcnt(0)
	s_barrier
	ds_read_b128 v[0:3], v193 offset:32768
	ds_read_b128 v[4:7], v193 offset:40960
	s_waitcnt vmcnt(7) lgkmcnt(1)
	v_mfma_f32_32x32x16_bf16 v[16:31], v[0:3], v[112:115], 0
	v_or_b32_e32 v0, 32, v208
	v_bitop3_b32 v0, v0, v68, v69 bitop3:0xde
	v_add_u32_e32 v198, 0, v0
	v_and_b32_e32 v12, 0x3fffffc0, v74
	v_lshl_add_u64 v[8:9], v[50:51], 0, s[28:29]
	s_mov_b64 s[28:29], 0x6000
	v_lshl_add_u64 v[10:11], v[50:51], 0, s[28:29]
	s_waitcnt lgkmcnt(0)
	v_mfma_f32_32x32x16_bf16 v[32:47], v[4:7], v[112:115], 0
	ds_read_b128 v[0:3], v198 offset:32768
	ds_read_b128 v[4:7], v198 offset:40960
	v_lshl_add_u32 v184, v12, 2, s3
	v_lshl_add_u64 v[12:13], s[42:43], 0, v[8:9]
	v_lshl_add_u64 v[14:15], s[42:43], 0, v[10:11]
	s_mov_b64 s[28:29], 0x8000
	s_cselect_b32 s3, 0, 0
	s_mov_b32 s76, s73
	s_waitcnt vmcnt(6) lgkmcnt(1)
	v_mfma_f32_32x32x16_bf16 v[16:31], v[0:3], v[108:111], v[16:31]
	v_or_b32_e32 v0, 64, v208
	v_bitop3_b32 v0, v0, v68, v69 bitop3:0xde
	v_add_u32_e32 v197, 0, v0
	s_mov_b32 s77, s73
	s_mov_b32 s78, s73
	s_mov_b32 s79, s73
	s_mov_b32 s80, s73
	s_waitcnt lgkmcnt(0)
	v_mfma_f32_32x32x16_bf16 v[32:47], v[4:7], v[108:111], v[32:47]
	ds_read_b128 v[0:3], v197 offset:32768
	ds_read_b128 v[4:7], v197 offset:40960
	s_mov_b32 s81, s73
	s_mov_b32 s82, s73
	s_mov_b32 s83, s73
	s_mov_b32 s84, s73
	s_mov_b32 s85, s73
	s_mov_b32 s86, s73
	s_waitcnt vmcnt(5) lgkmcnt(1)
	v_mfma_f32_32x32x16_bf16 v[16:31], v[0:3], v[120:123], v[16:31]
	v_or_b32_e32 v0, 0x60, v208
	v_bitop3_b32 v0, v0, v68, v69 bitop3:0xde
	v_add_u32_e32 v196, 0, v0
	s_mov_b32 s87, s73
	v_lshl_add_u32 v185, v179, 2, v184
	v_mov_b32_e32 v186, 0
	s_waitcnt lgkmcnt(0)
	v_mfma_f32_32x32x16_bf16 v[32:47], v[4:7], v[120:123], v[32:47]
	ds_read_b128 v[0:3], v196 offset:32768
	ds_read_b128 v[4:7], v196 offset:40960
	s_waitcnt vmcnt(4) lgkmcnt(1)
	v_mfma_f32_32x32x16_bf16 v[16:31], v[0:3], v[124:127], v[16:31]
	v_or_b32_e32 v0, 0x80, v208
	v_bitop3_b32 v0, v0, v68, v69 bitop3:0xde
	v_add_u32_e32 v194, 0, v0
	ds_read_b128 v[0:3], v194 offset:32768
	s_waitcnt lgkmcnt(1)
	v_mfma_f32_32x32x16_bf16 v[32:47], v[4:7], v[124:127], v[32:47]
	ds_read_b128 v[4:7], v194 offset:40960
	s_waitcnt vmcnt(3) lgkmcnt(1)
; #define SLOAD(i, k0) do { sr_[i].vs0 = St::ld8(&Vh[(long)((k0) + sr) * LDK + sc]); sr_[i].vs1 = St::ld8(&Vh[(long)((k0) + 32 + sr) * LDK + sc]); \
;     sr_[i].ks0 = St::ld8(&Kh[(long)((k0) + sr) * LDK + sc]); sr_[i].ks1 = St::ld8(&Kh[(long)((k0) + 32 + sr) * LDK + sc]); } while (0)
; #define SWAIT() do { if constexpr (SDEPTH == 2) asm volatile("s_waitcnt vmcnt(4)" ::: "memory"); else asm volatile("s_waitcnt vmcnt(0)" ::: "memory"); } while (0)
; __device__ __forceinline__ void partialSM(f32x16& p0, f32x16& p1, float& m_reg, float& mn, float& alpha) {
;   constexpr float C = SCALE * 1.4426950408889634f;
;   float pmax = p0[0]; for (int r = 1; r < 16; ++r) pmax = fmaxf(pmax, p0[r]); for (int r = 0; r < 16; ++r) pmax = fmaxf(pmax, p1[r]);
;   { auto rr = __builtin_amdgcn_permlane32_swap(__float_as_uint(pmax), __float_as_uint(pmax), false, false);
;     pmax = fmaxf(__uint_as_float(rr[0]), __uint_as_float(rr[1])); }
;   if (__builtin_expect(__all(pmax - m_reg <= THR / SCALE), 1)) { mn = m_reg; alpha = 1.f; }
;   else { mn = fmaxf(m_reg, pmax); alpha = __builtin_amdgcn_exp2f((m_reg - mn) * C); m_reg = mn; }
;   float mnC = -mn * C;
;   for (int r = 0; r < 16; ++r) p0[r] = fmaf(p0[r], C, mnC); for (int r = 0; r < 16; ++r) p1[r] = fmaf(p1[r], C, mnC);
;   for (int r = 0; r < 16; ++r) p0[r] = __builtin_amdgcn_exp2f(p0[r]);
; template <typename TQ>
; __device__ __forceinline__ void attn_dense_body(const TQ* __restrict__ Qb, const bf16* __restrict__ Kh, const bf16* __restrict__ Vh,
;                                                 unsigned short* __restrict__ Ob, int seq, char* lds) {
;     ...
;   SLOAD(SE, 0); asm volatile("s_waitcnt vmcnt(0)" ::: "memory"); SWRITE(0, SE); __syncthreads();
;   qkt(pA0, pA1, K_lds, qr, r32, hi); partialSM(pA0, pA1, m_reg, mnA, alA);
;   SLOAD(SO, KVBLK); if constexpr (SDEPTH == 2) { if (2 < NT) SLOAD(SE, 2 * KVBLK); }
;   SWAIT(); SWRITE(1, SO); __syncthreads();
	v_mfma_f32_32x32x16_bf16 v[16:31], v[0:3], v[116:119], v[16:31]
	v_or_b32_e32 v0, 0xa0, v208
	v_bitop3_b32 v0, v0, v68, v69 bitop3:0xde
	v_add_u32_e32 v195, 0, v0
	ds_read_b128 v[0:3], v195 offset:32768
	s_waitcnt lgkmcnt(1)
	v_mfma_f32_32x32x16_bf16 v[32:47], v[4:7], v[116:119], v[32:47]
	ds_read_b128 v[4:7], v195 offset:40960
	global_load_dwordx4 v[52:55], v[12:13], off
	global_load_dwordx4 v[56:59], v[14:15], off
	s_waitcnt vmcnt(4) lgkmcnt(1)
	v_mfma_f32_32x32x16_bf16 v[16:31], v[0:3], v[104:107], v[16:31]
	v_lshl_add_u64 v[0:1], s[38:39], 0, v[8:9]
	v_lshl_add_u64 v[2:3], s[38:39], 0, v[10:11]
	global_load_dwordx4 v[60:63], v[0:1], off
	global_load_dwordx4 v[64:67], v[2:3], off
	v_or_b32_e32 v0, 0xc0, v208
	v_bitop3_b32 v0, v0, v68, v69 bitop3:0xde
	v_add_u32_e32 v200, 0, v0
	ds_read_b128 v[0:3], v200 offset:32768
	v_lshlrev_b32_e32 v9, 1, v74
	v_and_or_b32 v8, v70, 24, v71
	s_waitcnt lgkmcnt(1)
	v_mfma_f32_32x32x16_bf16 v[32:47], v[4:7], v[104:107], v[32:47]
	v_and_b32_e32 v4, 32, v9
	v_and_b32_e32 v5, 0x100, v70
	v_or3_b32 v75, v8, v4, v5
	ds_read_b128 v[4:7], v200 offset:40960
	v_add_u32_e32 v188, s3, v75
	s_waitcnt vmcnt(5) lgkmcnt(1)
	v_mfma_f32_32x32x16_bf16 v[16:31], v[0:3], v[100:103], v[16:31]
	v_or_b32_e32 v0, 0xe0, v208
	v_bitop3_b32 v0, v0, v68, v69 bitop3:0xde
	v_add_u32_e32 v199, 0, v0
	ds_read_b128 v[0:3], v199 offset:32768
	ds_read_b128 v[68:71], v199 offset:40960
	s_waitcnt lgkmcnt(2)
	v_mfma_f32_32x32x16_bf16 v[32:47], v[4:7], v[100:103], v[32:47]
	s_waitcnt vmcnt(4) lgkmcnt(1)
	v_mfma_f32_32x32x16_bf16 v[16:31], v[0:3], v[96:99], v[16:31]
	v_mov_b64_e32 v[0:1], s[72:73]
	v_mov_b64_e32 v[14:15], s[86:87]
	v_mov_b64_e32 v[2:3], s[74:75]
	v_mov_b64_e32 v[4:5], s[76:77]
	v_mov_b64_e32 v[6:7], s[78:79]
	v_mov_b64_e32 v[8:9], s[80:81]
	v_mov_b64_e32 v[10:11], s[82:83]
	s_waitcnt lgkmcnt(0)
	v_mfma_f32_32x32x16_bf16 v[32:47], v[68:71], v[96:99], v[32:47]
	s_nop 2
	v_max_f32_e32 v68, v17, v17
	v_max_f32_e32 v69, v16, v16
	v_max_f32_e32 v68, v69, v68
	v_max3_f32 v68, v68, v18, v19
	v_max3_f32 v68, v68, v20, v21
	v_max3_f32 v68, v68, v22, v23
	v_max3_f32 v68, v68, v24, v25
	v_max3_f32 v68, v68, v26, v27
	v_max3_f32 v68, v68, v28, v29
	v_max3_f32 v68, v68, v30, v31
	v_max3_f32 v68, v68, v32, v33
	v_max3_f32 v68, v68, v34, v35
	v_max3_f32 v68, v68, v36, v37
	v_max3_f32 v68, v68, v38, v39
	v_max3_f32 v68, v68, v40, v41
	v_max3_f32 v68, v68, v42, v43
	v_max3_f32 v76, v68, v44, v45
	v_lshl_add_u64 v[68:69], v[50:51], 0, s[28:29]
	s_mov_b64 s[28:29], 0xa000
	v_lshl_add_u64 v[70:71], s[42:43], 0, v[68:69]
	v_lshl_add_u64 v[50:51], v[50:51], 0, s[28:29]
	v_lshl_add_u64 v[68:69], s[38:39], 0, v[68:69]
	v_lshl_add_u64 v[72:73], s[42:43], 0, v[50:51]
	global_load_dwordx4 v[128:131], v[70:71], off
	global_load_dwordx4 v[136:139], v[72:73], off
	v_lshl_add_u64 v[50:51], s[38:39], 0, v[50:51]
	global_load_dwordx4 v[132:135], v[68:69], off
	global_load_dwordx4 v[140:143], v[50:51], off
	v_max3_f32 v50, v76, v46, v47
	v_mov_b32_e32 v51, v50
	s_nop 1
	v_permlane32_swap_b32_e32 v50, v51
	v_max_f32_e32 v51, v51, v51
	v_max_f32_e32 v50, v50, v50
	v_max_f32_e32 v50, v50, v51
	v_add_f32_e32 v51, 0x7149f2ca, v50
	v_max_f32_e32 v50, 0xf149f2ca, v50
	v_cmp_ge_f32_e32 vcc, s4, v51
	v_sub_f32_e32 v51, 0xf149f2ca, v50
	v_mul_f32_e32 v51, 0x3e0293ee, v51
	v_exp_f32_e32 v51, v51
	s_cmp_eq_u64 vcc, exec
	s_cselect_b64 vcc, -1, 0
	s_addk_i32 s3, 0x4000
	v_cndmask_b32_e64 v201, v51, 1.0, vcc
	v_mov_b32_e32 v51, 0xf149f2ca
	v_cndmask_b32_e32 v168, v50, v51, vcc
	v_mul_f32_e32 v50, 0xbe0293ee, v168
	v_fmamk_f32 v16, v16, 0x3e0293ee, v50
	v_exp_f32_e32 v161, v16
	v_fmamk_f32 v16, v17, 0x3e0293ee, v50
	v_exp_f32_e32 v175, v16
	v_fmamk_f32 v16, v18, 0x3e0293ee, v50
	v_exp_f32_e32 v162, v16
	v_fmamk_f32 v16, v19, 0x3e0293ee, v50
	v_exp_f32_e32 v205, v16
	v_fmamk_f32 v16, v20, 0x3e0293ee, v50
	v_exp_f32_e32 v174, v16
	v_fmamk_f32 v16, v21, 0x3e0293ee, v50
	v_exp_f32_e32 v214, v16
	v_fmamk_f32 v16, v22, 0x3e0293ee, v50
	v_exp_f32_e32 v163, v16
	v_fmamk_f32 v16, v23, 0x3e0293ee, v50
	v_exp_f32_e32 v173, v16
	v_fmamk_f32 v16, v24, 0x3e0293ee, v50
	v_exp_f32_e32 v164, v16
	v_fmamk_f32 v16, v25, 0x3e0293ee, v50
	v_exp_f32_e32 v171, v16
	v_fmamk_f32 v16, v26, 0x3e0293ee, v50
	v_exp_f32_e32 v165, v16
	v_fmamk_f32 v16, v27, 0x3e0293ee, v50
	v_exp_f32_e32 v172, v16
	v_fmamk_f32 v16, v28, 0x3e0293ee, v50
	v_exp_f32_e32 v166, v16
	v_fmamk_f32 v16, v29, 0x3e0293ee, v50
	v_pk_fma_f32 v[144:145], v[46:47], s[22:23], v[50:51] op_sel_hi:[1,0,0]
	v_pk_fma_f32 v[150:151], v[44:45], s[22:23], v[50:51] op_sel_hi:[1,0,0]
	v_pk_fma_f32 v[154:155], v[42:43], s[22:23], v[50:51] op_sel_hi:[1,0,0]
	v_pk_fma_f32 v[146:147], v[40:41], s[22:23], v[50:51] op_sel_hi:[1,0,0]
	v_pk_fma_f32 v[148:149], v[38:39], s[22:23], v[50:51] op_sel_hi:[1,0,0]
	v_pk_fma_f32 v[152:153], v[36:37], s[22:23], v[50:51] op_sel_hi:[1,0,0]
	v_pk_fma_f32 v[156:157], v[34:35], s[22:23], v[50:51] op_sel_hi:[1,0,0]
	v_pk_fma_f32 v[158:159], v[32:33], s[22:23], v[50:51] op_sel_hi:[1,0,0]
	v_exp_f32_e32 v169, v16
	v_fmamk_f32 v16, v30, 0x3e0293ee, v50
	v_fmac_f32_e32 v50, 0x3e0293ee, v31
	v_add_u32_e32 v187, s3, v75
	v_readlane_b32 s3, v253, 29
	v_exp_f32_e32 v167, v16
	v_exp_f32_e32 v170, v50
	v_and_b32_e32 v16, 15, v74
	s_add_u32 s0, s3, s0
	v_readlane_b32 s3, v253, 30
	s_waitcnt vmcnt(4)
	v_lshl_or_b32 v48, v16, 4, v48
	s_addc_u32 s1, s3, s1
	v_mov_b64_e32 v[12:13], s[84:85]
	s_waitcnt vmcnt(7)
	ds_write_b128 v191, v[52:55] offset:16384
	s_waitcnt vmcnt(6)
	ds_write_b128 v192, v[56:59] offset:16384
	s_waitcnt vmcnt(5)
	ds_write_b128 v189, v[60:63] offset:49152
	s_waitcnt vmcnt(4)
	ds_write_b128 v190, v[64:67] offset:49152
	v_lshl_add_u64 v[180:181], s[0:1], 0, v[48:49]
	v_mov_b64_e32 v[62:63], v[14:15]
	v_mov_b64_e32 v[46:47], v[14:15]
	v_mov_b64_e32 v[30:31], v[14:15]
	v_readlane_b32 s84, v252, 4
	v_cmp_gt_u32_e64 s[38:39], 32, v177
	v_mov_b64_e32 v[60:61], v[12:13]
	v_mov_b64_e32 v[58:59], v[10:11]
	v_mov_b64_e32 v[56:57], v[8:9]
	v_mov_b64_e32 v[54:55], v[6:7]
	v_mov_b64_e32 v[52:53], v[4:5]
	v_mov_b64_e32 v[50:51], v[2:3]
	v_mov_b64_e32 v[48:49], v[0:1]
	v_mov_b64_e32 v[44:45], v[12:13]
	v_mov_b64_e32 v[42:43], v[10:11]
	v_mov_b64_e32 v[40:41], v[8:9]
	v_mov_b64_e32 v[38:39], v[6:7]
	v_mov_b64_e32 v[36:37], v[4:5]
	v_mov_b64_e32 v[34:35], v[2:3]
	v_mov_b64_e32 v[32:33], v[0:1]
	v_mov_b64_e32 v[28:29], v[12:13]
	v_mov_b64_e32 v[26:27], v[10:11]
	v_mov_b64_e32 v[24:25], v[8:9]
	v_mov_b64_e32 v[22:23], v[6:7]
	v_mov_b64_e32 v[20:21], v[4:5]
	v_mov_b64_e32 v[18:19], v[2:3]
	v_mov_b64_e32 v[16:17], v[0:1]
	v_readlane_b32 s85, v252, 5
	v_readlane_b32 s86, v252, 6
	s_mov_b32 s74, 0x7f800000
	s_mov_b32 s75, 0x2b000
	s_mov_b64 s[78:79], 0x800
	s_movk_i32 s77, 0x1ff
	s_waitcnt lgkmcnt(0)
	s_barrier
; __device__ __forceinline__ int v_st(int k, int c) { const int kk = (k & ~0xC) | ((k & 4) << 1) | ((k & 8) >> 1); return ((kk >> 3) * 4 + (c >> 5)) * 512 + ((kk & 7) * 32 + (c & 31)) * 2; }
; __device__ __forceinline__ int v_rd_base(int lane) { return ((lane & 3) << 3) | (((lane >> 2) & 3) << 6) | (((lane >> 4) & 1) << 5) | (((lane >> 5) & 1) << 8); }
; #define SLOAD(i, k0) do { sr_[i].vs0 = St::ld8(&Vh[(long)((k0) + sr) * LDK + sc]); sr_[i].vs1 = St::ld8(&Vh[(long)((k0) + 32 + sr) * LDK + sc]); \
;     sr_[i].ks0 = St::ld8(&Kh[(long)((k0) + sr) * LDK + sc]); sr_[i].ks1 = St::ld8(&Kh[(long)((k0) + 32 + sr) * LDK + sc]); } while (0)
; #define SWAIT() do { if constexpr (SDEPTH == 2) asm volatile("s_waitcnt vmcnt(4)" ::: "memory"); else asm volatile("s_waitcnt vmcnt(0)" ::: "memory"); } while (0)
; template <typename TQ>
; __device__ __forceinline__ void attn_dense_body(const TQ* __restrict__ Qb, const bf16* __restrict__ Kh, const bf16* __restrict__ Vh,
;                                                 unsigned short* __restrict__ Ob, int seq, char* lds) {
;     ...
;   const int sr = tid >> 4, sc = (tid & 15) * 8, vst0 = v_st(sr, sc), vst1 = v_st(32 + sr, sc);
;   const int vb0 = (int)(uintptr_t)V_lds + v_rd_base(lane);
;   struct { typename St::T vs0, vs1, ks0, ks1; } sr_[SDEPTH];
;     ...
;   f32x16 pA0, pA1, pB0, pB1; float mnA, mnB, alA, alB; bf16x8 pa0, pa1, pa2, pa3; const int NT = seq / KVBLK;
;   constexpr int SE = 0, SO = SDEPTH - 1;
;   SLOAD(SE, 0); asm volatile("s_waitcnt vmcnt(0)" ::: "memory"); SWRITE(0, SE); __syncthreads();
;   qkt(pA0, pA1, K_lds, qr, r32, hi); partialSM(pA0, pA1, m_reg, mnA, alA);
;   SLOAD(SO, KVBLK); if constexpr (SDEPTH == 2) { if (2 < NT) SLOAD(SE, 2 * KVBLK); }
;   SWAIT(); SWRITE(1, SO); __syncthreads();
;   for (int j = 1; j + 1 < NT; j += 2) {
	v_readlane_b32 s87, v252, 7
	s_waitcnt vmcnt(0)
	v_add_u32_e32 v136, 0x10000, v189
	v_add_u32_e32 v137, 0x10000, v190
	ds_write_b128 v136, v[132:135] offset:32768
	ds_write_b128 v137, v[140:143] offset:32768
	v_lshrrev_b32_e32 v138, 6, v211
	v_lshrrev_b32_e32 v139, 4, v246
	v_lshl_add_u32 v139, v138, 3, v139
	v_and_b32_e32 v129, 15, v246
	v_and_b32_e32 v128, 7, v139
	v_xor_b32_e32 v129, v129, v128
	v_lshlrev_b32_e32 v129, 4, v129
	v_lshl_add_u32 v128, v139, 8, v129
	v_xor_b32_e32 v129, 64, v129
	v_add_u32_e32 v139, 4, v139
	v_lshl_add_u32 v129, v139, 8, v129
	s_nop 1
	v_and_b32_e32 v136, 6, v138
	v_lshlrev_b32_e32 v136, 3, v136
	v_bfe_u32 v137, v246, 2, 2
	v_add_u32_e32 v136, v136, v137
	v_bfe_u32 v137, v246, 4, 1
	v_lshl_add_u32 v136, v137, 3, v136
	v_and_b32_e32 v137, 1, v138
	v_lshl_add_u32 v136, v137, 2, v136
	v_lshlrev_b32_e32 v136, 8, v136
	v_bfe_u32 v137, v246, 5, 1
	v_lshl_add_u32 v136, v137, 6, v136
	v_and_b32_e32 v137, 3, v246
	v_lshl_add_u32 v130, v137, 4, v136
	v_add_u32_e32 v131, 0x80, v130
	v_readfirstlane_b32 s5, v211
	s_nop 3
	s_lshr_b32 s5, s5, 6
	s_lshl_b32 s5, s5, 11
	s_mov_b32 s28, 0
	s_mov_b32 s29, 0x10000
	s_add_u32 s6, s6, 0xc000
	s_addc_u32 s7, s7, 0
	s_add_u32 s68, s68, 0x8000
	s_addc_u32 s69, s69, 0
	s_add_i32 m0, s5, 0x1c000
	s_nop 0
	global_load_lds_dwordx4 v128, s[6:7]
	s_add_i32 m0, s5, 0x1c400
	s_nop 0
	global_load_lds_dwordx4 v129, s[6:7]
	s_add_i32 m0, s5, 0x10000
	s_nop 0
	global_load_lds_dwordx4 v130, s[68:69]
	s_add_i32 m0, s5, 0x10400
	s_nop 0
	global_load_lds_dwordx4 v131, s[68:69]
	s_add_u32 s6, s6, 0x4000
	s_addc_u32 s7, s7, 0
	s_add_u32 s68, s68, 0x4000
	s_addc_u32 s69, s69, 0
	s_cmp_ge_u32 s5, 0x2000
	s_cbranch_scc0 .Latt_lead
	s_waitcnt lgkmcnt(0)
	s_barrier
	s_branch .Latt_skipE0
.Latt_lead:
	s_setprio 1
